# EpiQKV0 epilogue regenerated: sumsq and rotary loads upfront, one wait, 32 stores with no waits between
# speedup vs baseline: 1.0113x; 1.0002x over previous
.LBB0_107:
	ds_read_b128 v[128:131], v170
	ds_read_b128 v[132:135], v170 offset:1024
	ds_read_b128 v[152:155], v170 offset:2048
	ds_read_b128 v[156:159], v170 offset:3072
	s_add_u32 s16, s14, 0xfff80080
	s_addc_u32 s17, s15, -1
	s_cmp_eq_u32 s81, 28
	s_cselect_b32 s19, s9, s17
	s_cselect_b32 s18, s13, s16
	s_cselect_b32 s17, s49, s69
	s_cselect_b32 s16, s55, s68
	v_lshl_add_u64 v[202:203], s[14:15], 0, v[144:145]
	s_add_i32 m0, s26, 0xc000
	ds_read_b128 v[160:163], v171
	ds_read_b128 v[174:177], v171 offset:1024
	ds_read_b128 v[178:181], v171 offset:2048
	ds_read_b128 v[182:185], v171 offset:3072
	ds_read_b128 v[186:189], v171 offset:4096
	ds_read_b128 v[190:193], v171 offset:5120
	ds_read_b128 v[194:197], v171 offset:6144
	ds_read_b128 v[198:201], v171 offset:7168
	global_load_lds_dwordx4 v[202:203], off
	v_lshl_add_u64 v[202:203], s[14:15], 0, v[146:147]
	s_add_i32 m0, s26, 0xe000
	s_nop 0
	global_load_lds_dwordx4 v[202:203], off
	s_waitcnt lgkmcnt(8)
	s_barrier
	s_waitcnt lgkmcnt(0)
	s_setprio 1
	s_waitcnt lgkmcnt(0)
	v_mfma_f32_16x16x32_bf16 v[124:127], v[128:131], v[160:163], v[124:127]
	v_mfma_f32_16x16x32_bf16 v[120:123], v[152:155], v[160:163], v[120:123]
	v_mfma_f32_16x16x32_bf16 v[108:111], v[128:131], v[178:181], v[108:111]
	v_mfma_f32_16x16x32_bf16 v[104:107], v[152:155], v[178:181], v[104:107]
	v_mfma_f32_16x16x32_bf16 v[92:95], v[128:131], v[186:189], v[92:95]
	v_mfma_f32_16x16x32_bf16 v[88:91], v[152:155], v[186:189], v[88:91]
	v_mfma_f32_16x16x32_bf16 v[76:79], v[128:131], v[194:197], v[76:79]
	v_mfma_f32_16x16x32_bf16 v[72:75], v[152:155], v[194:197], v[72:75]
	v_mfma_f32_16x16x32_bf16 v[124:127], v[132:135], v[174:177], v[124:127]
	v_mfma_f32_16x16x32_bf16 v[120:123], v[156:159], v[174:177], v[120:123]
	v_mfma_f32_16x16x32_bf16 v[108:111], v[132:135], v[182:185], v[108:111]
	v_mfma_f32_16x16x32_bf16 v[104:107], v[156:159], v[182:185], v[104:107]
	v_mfma_f32_16x16x32_bf16 v[92:95], v[132:135], v[190:193], v[92:95]
	v_mfma_f32_16x16x32_bf16 v[88:91], v[156:159], v[190:193], v[88:91]
	v_mfma_f32_16x16x32_bf16 v[76:79], v[132:135], v[198:201], v[76:79]
	v_mfma_f32_16x16x32_bf16 v[72:75], v[156:159], v[198:201], v[72:75]
	s_setprio 0
	s_barrier
	s_add_i32 s82, s72, s5
	v_lshl_add_u64 v[218:219], s[16:17], 0, v[138:139]
	s_mov_b32 m0, s82
	ds_read_b128 v[202:205], v172
	ds_read_b128 v[206:209], v172 offset:1024
	ds_read_b128 v[210:213], v172 offset:2048
	ds_read_b128 v[214:217], v172 offset:3072
	global_load_lds_dwordx4 v[218:219], off
	v_lshl_add_u64 v[220:221], s[16:17], 0, v[140:141]
	s_add_i32 m0, s82, 0x2000
	s_nop 0
	global_load_lds_dwordx4 v[220:221], off
	s_barrier
	s_waitcnt lgkmcnt(0)
	s_setprio 1
	s_waitcnt lgkmcnt(0)
	v_mfma_f32_16x16x32_bf16 v[116:119], v[202:205], v[160:163], v[116:119]
	v_mfma_f32_16x16x32_bf16 v[112:115], v[210:213], v[160:163], v[112:115]
	v_mfma_f32_16x16x32_bf16 v[100:103], v[202:205], v[178:181], v[100:103]
	v_mfma_f32_16x16x32_bf16 v[96:99], v[210:213], v[178:181], v[96:99]
	v_mfma_f32_16x16x32_bf16 v[84:87], v[202:205], v[186:189], v[84:87]
	v_mfma_f32_16x16x32_bf16 v[80:83], v[210:213], v[186:189], v[80:83]
	v_mfma_f32_16x16x32_bf16 v[68:71], v[202:205], v[194:197], v[68:71]
	v_mfma_f32_16x16x32_bf16 v[64:67], v[210:213], v[194:197], v[64:67]
	v_mfma_f32_16x16x32_bf16 v[116:119], v[206:209], v[174:177], v[116:119]
	v_mfma_f32_16x16x32_bf16 v[112:115], v[214:217], v[174:177], v[112:115]
	v_mfma_f32_16x16x32_bf16 v[100:103], v[206:209], v[182:185], v[100:103]
	v_mfma_f32_16x16x32_bf16 v[96:99], v[214:217], v[182:185], v[96:99]
	v_mfma_f32_16x16x32_bf16 v[84:87], v[206:209], v[190:193], v[84:87]
	v_mfma_f32_16x16x32_bf16 v[80:83], v[214:217], v[190:193], v[80:83]
	v_mfma_f32_16x16x32_bf16 v[68:71], v[206:209], v[198:201], v[68:71]
	v_mfma_f32_16x16x32_bf16 v[64:67], v[214:217], v[198:201], v[64:67]
	s_setprio 0
	s_mov_b32 m0, s26
	v_lshl_add_u64 v[222:223], s[18:19], 0, v[138:139]
	s_barrier
	ds_read_b128 v[160:163], v171 offset:16384
	ds_read_b128 v[174:177], v171 offset:17408
	ds_read_b128 v[178:181], v171 offset:18432
	ds_read_b128 v[182:185], v171 offset:19456
	ds_read_b128 v[186:189], v171 offset:20480
	ds_read_b128 v[190:193], v171 offset:21504
	ds_read_b128 v[194:197], v171 offset:22528
	ds_read_b128 v[198:201], v171 offset:23552
	global_load_lds_dwordx4 v[222:223], off
	v_lshl_add_u64 v[224:225], s[18:19], 0, v[140:141]
	s_mov_b32 m0, s27
	s_nop 0
	global_load_lds_dwordx4 v[224:225], off
	s_barrier
	s_waitcnt lgkmcnt(0)
	s_setprio 1
	s_waitcnt lgkmcnt(0)
	v_mfma_f32_16x16x32_bf16 v[60:63], v[128:131], v[160:163], v[60:63]
	v_mfma_f32_16x16x32_bf16 v[56:59], v[152:155], v[160:163], v[56:59]
	v_mfma_f32_16x16x32_bf16 v[44:47], v[128:131], v[178:181], v[44:47]
	v_mfma_f32_16x16x32_bf16 v[40:43], v[152:155], v[178:181], v[40:43]
	v_mfma_f32_16x16x32_bf16 v[28:31], v[128:131], v[186:189], v[28:31]
	v_mfma_f32_16x16x32_bf16 v[24:27], v[152:155], v[186:189], v[24:27]
	v_mfma_f32_16x16x32_bf16 v[12:15], v[128:131], v[194:197], v[12:15]
	v_mfma_f32_16x16x32_bf16 v[8:11], v[152:155], v[194:197], v[8:11]
	v_mfma_f32_16x16x32_bf16 v[60:63], v[132:135], v[174:177], v[60:63]
	v_mfma_f32_16x16x32_bf16 v[56:59], v[156:159], v[174:177], v[56:59]
	v_mfma_f32_16x16x32_bf16 v[44:47], v[132:135], v[182:185], v[44:47]
	v_mfma_f32_16x16x32_bf16 v[40:43], v[156:159], v[182:185], v[40:43]
	v_mfma_f32_16x16x32_bf16 v[28:31], v[132:135], v[190:193], v[28:31]
	v_mfma_f32_16x16x32_bf16 v[24:27], v[156:159], v[190:193], v[24:27]
	v_mfma_f32_16x16x32_bf16 v[12:15], v[132:135], v[198:201], v[12:15]
	v_mfma_f32_16x16x32_bf16 v[8:11], v[156:159], v[198:201], v[8:11]
	s_setprio 0
	s_barrier
	s_add_u32 s82, s16, 0x80000
	s_addc_u32 s83, s17, 0
	s_add_i32 s84, s73, s5
	v_lshl_add_u64 v[128:129], s[82:83], 0, v[138:139]
	s_mov_b32 m0, s84
	s_nop 0
	global_load_lds_dwordx4 v[128:129], off
	v_lshl_add_u64 v[128:129], s[82:83], 0, v[140:141]
	s_add_i32 m0, s84, 0x2000
	s_nop 0
	global_load_lds_dwordx4 v[128:129], off
	s_waitcnt vmcnt(6)
	s_barrier
	s_setprio 1
	v_mfma_f32_16x16x32_bf16 v[52:55], v[202:205], v[160:163], v[52:55]
	v_mfma_f32_16x16x32_bf16 v[48:51], v[210:213], v[160:163], v[48:51]
	v_mfma_f32_16x16x32_bf16 v[36:39], v[202:205], v[178:181], v[36:39]
	v_mfma_f32_16x16x32_bf16 v[32:35], v[210:213], v[178:181], v[32:35]
	v_mfma_f32_16x16x32_bf16 v[20:23], v[202:205], v[186:189], v[20:23]
	v_mfma_f32_16x16x32_bf16 v[16:19], v[210:213], v[186:189], v[16:19]
	v_mfma_f32_16x16x32_bf16 v[4:7], v[202:205], v[194:197], v[4:7]
	v_mfma_f32_16x16x32_bf16 v[0:3], v[210:213], v[194:197], v[0:3]
	v_mfma_f32_16x16x32_bf16 v[52:55], v[206:209], v[174:177], v[52:55]
	v_mfma_f32_16x16x32_bf16 v[48:51], v[214:217], v[174:177], v[48:51]
	v_mfma_f32_16x16x32_bf16 v[36:39], v[206:209], v[182:185], v[36:39]
	v_mfma_f32_16x16x32_bf16 v[32:35], v[214:217], v[182:185], v[32:35]
	v_mfma_f32_16x16x32_bf16 v[20:23], v[206:209], v[190:193], v[20:23]
	v_mfma_f32_16x16x32_bf16 v[16:19], v[214:217], v[190:193], v[16:19]
	v_mfma_f32_16x16x32_bf16 v[4:7], v[206:209], v[198:201], v[4:7]
	v_mfma_f32_16x16x32_bf16 v[0:3], v[214:217], v[198:201], v[0:3]
	s_setprio 0
	s_add_i32 s82, 16, 0x18000
	v_add_u32_e32 v156, s82, v166
	s_barrier
	ds_read_b128 v[128:131], v156
	ds_read_b128 v[132:135], v156 offset:1024
	ds_read_b128 v[152:155], v156 offset:2048
	ds_read_b128 v[156:159], v156 offset:3072
	s_add_u32 s18, s18, 0x80000
	s_addc_u32 s19, s19, 0
	s_mov_b32 m0, s39
	v_lshl_add_u64 v[202:203], s[18:19], 0, v[138:139]
	ds_read_b128 v[160:163], v171 offset:32768
	ds_read_b128 v[174:177], v171 offset:33792
	ds_read_b128 v[178:181], v171 offset:34816
	ds_read_b128 v[182:185], v171 offset:35840
	ds_read_b128 v[186:189], v171 offset:36864
	ds_read_b128 v[190:193], v171 offset:37888
	ds_read_b128 v[194:197], v171 offset:38912
	ds_read_b128 v[198:201], v171 offset:39936
	global_load_lds_dwordx4 v[202:203], off
	v_lshl_add_u64 v[202:203], s[18:19], 0, v[140:141]
	s_mov_b32 m0, s47
	s_nop 0
	global_load_lds_dwordx4 v[202:203], off
	s_waitcnt lgkmcnt(8)
	s_barrier
	s_waitcnt lgkmcnt(0)
	s_setprio 1
	s_waitcnt lgkmcnt(0)
	v_mfma_f32_16x16x32_bf16 v[124:127], v[128:131], v[160:163], v[124:127]
	v_mfma_f32_16x16x32_bf16 v[120:123], v[152:155], v[160:163], v[120:123]
	v_mfma_f32_16x16x32_bf16 v[108:111], v[128:131], v[178:181], v[108:111]
	v_mfma_f32_16x16x32_bf16 v[104:107], v[152:155], v[178:181], v[104:107]
	v_mfma_f32_16x16x32_bf16 v[92:95], v[128:131], v[186:189], v[92:95]
	v_mfma_f32_16x16x32_bf16 v[88:91], v[152:155], v[186:189], v[88:91]
	v_mfma_f32_16x16x32_bf16 v[76:79], v[128:131], v[194:197], v[76:79]
	v_mfma_f32_16x16x32_bf16 v[72:75], v[152:155], v[194:197], v[72:75]
	v_mfma_f32_16x16x32_bf16 v[124:127], v[132:135], v[174:177], v[124:127]
	v_mfma_f32_16x16x32_bf16 v[120:123], v[156:159], v[174:177], v[120:123]
	v_mfma_f32_16x16x32_bf16 v[108:111], v[132:135], v[182:185], v[108:111]
	v_mfma_f32_16x16x32_bf16 v[104:107], v[156:159], v[182:185], v[104:107]
	v_mfma_f32_16x16x32_bf16 v[92:95], v[132:135], v[190:193], v[92:95]
	v_mfma_f32_16x16x32_bf16 v[88:91], v[156:159], v[190:193], v[88:91]
	v_mfma_f32_16x16x32_bf16 v[76:79], v[132:135], v[198:201], v[76:79]
	v_mfma_f32_16x16x32_bf16 v[72:75], v[156:159], v[198:201], v[72:75]
	s_setprio 0
	s_barrier
	s_add_i32 s18, 16, 0x1c000
	s_add_i32 s19, s82, s5
	v_add_u32_e32 v214, s18, v166
	v_lshl_add_u64 v[218:219], v[218:219], 0, s[24:25]
	s_mov_b32 m0, s19
	ds_read_b128 v[202:205], v214
	ds_read_b128 v[206:209], v214 offset:1024
	ds_read_b128 v[210:213], v214 offset:2048
	ds_read_b128 v[214:217], v214 offset:3072
	global_load_lds_dwordx4 v[218:219], off
	v_lshl_add_u64 v[218:219], v[220:221], 0, s[24:25]
	s_add_i32 m0, s19, 0x2000
	s_nop 0
	global_load_lds_dwordx4 v[218:219], off
	s_barrier
	s_waitcnt lgkmcnt(0)
	s_setprio 1
	s_waitcnt lgkmcnt(0)
	v_mfma_f32_16x16x32_bf16 v[116:119], v[202:205], v[160:163], v[116:119]
	v_mfma_f32_16x16x32_bf16 v[112:115], v[210:213], v[160:163], v[112:115]
	v_mfma_f32_16x16x32_bf16 v[100:103], v[202:205], v[178:181], v[100:103]
	v_mfma_f32_16x16x32_bf16 v[96:99], v[210:213], v[178:181], v[96:99]
	v_mfma_f32_16x16x32_bf16 v[84:87], v[202:205], v[186:189], v[84:87]
	v_mfma_f32_16x16x32_bf16 v[80:83], v[210:213], v[186:189], v[80:83]
	v_mfma_f32_16x16x32_bf16 v[68:71], v[202:205], v[194:197], v[68:71]
	v_mfma_f32_16x16x32_bf16 v[64:67], v[210:213], v[194:197], v[64:67]
	v_mfma_f32_16x16x32_bf16 v[116:119], v[206:209], v[174:177], v[116:119]
	v_mfma_f32_16x16x32_bf16 v[112:115], v[214:217], v[174:177], v[112:115]
	v_mfma_f32_16x16x32_bf16 v[100:103], v[206:209], v[182:185], v[100:103]
	v_mfma_f32_16x16x32_bf16 v[96:99], v[214:217], v[182:185], v[96:99]
	v_mfma_f32_16x16x32_bf16 v[84:87], v[206:209], v[190:193], v[84:87]
	v_mfma_f32_16x16x32_bf16 v[80:83], v[214:217], v[190:193], v[80:83]
	v_mfma_f32_16x16x32_bf16 v[68:71], v[206:209], v[198:201], v[68:71]
	v_mfma_f32_16x16x32_bf16 v[64:67], v[214:217], v[198:201], v[64:67]
	s_setprio 0
	s_mov_b32 m0, s56
	v_lshl_add_u64 v[218:219], v[222:223], 0, s[24:25]
	s_barrier
	ds_read_b128 v[160:163], v171 offset:49152
	ds_read_b128 v[174:177], v171 offset:50176
	ds_read_b128 v[178:181], v171 offset:51200
	ds_read_b128 v[182:185], v171 offset:52224
	ds_read_b128 v[186:189], v171 offset:53248
	ds_read_b128 v[190:193], v171 offset:54272
	ds_read_b128 v[194:197], v171 offset:55296
	ds_read_b128 v[198:201], v171 offset:56320
	global_load_lds_dwordx4 v[218:219], off
	v_lshl_add_u64 v[218:219], v[224:225], 0, s[24:25]
	s_mov_b32 m0, s57
	s_nop 0
	global_load_lds_dwordx4 v[218:219], off
	s_barrier
	s_waitcnt lgkmcnt(0)
	s_setprio 1
	s_waitcnt lgkmcnt(0)
	v_mfma_f32_16x16x32_bf16 v[60:63], v[128:131], v[160:163], v[60:63]
	v_mfma_f32_16x16x32_bf16 v[56:59], v[152:155], v[160:163], v[56:59]
	v_mfma_f32_16x16x32_bf16 v[44:47], v[128:131], v[178:181], v[44:47]
	v_mfma_f32_16x16x32_bf16 v[40:43], v[152:155], v[178:181], v[40:43]
	v_mfma_f32_16x16x32_bf16 v[28:31], v[128:131], v[186:189], v[28:31]
	v_mfma_f32_16x16x32_bf16 v[24:27], v[152:155], v[186:189], v[24:27]
	v_mfma_f32_16x16x32_bf16 v[12:15], v[128:131], v[194:197], v[12:15]
	v_mfma_f32_16x16x32_bf16 v[8:11], v[152:155], v[194:197], v[8:11]
	v_mfma_f32_16x16x32_bf16 v[60:63], v[132:135], v[174:177], v[60:63]
	v_mfma_f32_16x16x32_bf16 v[56:59], v[156:159], v[174:177], v[56:59]
	v_mfma_f32_16x16x32_bf16 v[44:47], v[132:135], v[182:185], v[44:47]
	v_mfma_f32_16x16x32_bf16 v[40:43], v[156:159], v[182:185], v[40:43]
	v_mfma_f32_16x16x32_bf16 v[28:31], v[132:135], v[190:193], v[28:31]
	v_mfma_f32_16x16x32_bf16 v[24:27], v[156:159], v[190:193], v[24:27]
	v_mfma_f32_16x16x32_bf16 v[12:15], v[132:135], v[198:201], v[12:15]
	v_mfma_f32_16x16x32_bf16 v[8:11], v[156:159], v[198:201], v[8:11]
	s_setprio 0
	s_barrier
	s_add_u32 s16, s16, 0x80080
	s_addc_u32 s17, s17, 0
	s_add_i32 s18, s18, s5
	v_lshl_add_u64 v[128:129], s[16:17], 0, v[138:139]
	s_mov_b32 m0, s18
	s_nop 0
	global_load_lds_dwordx4 v[128:129], off
	v_lshl_add_u64 v[128:129], s[16:17], 0, v[140:141]
	s_add_i32 m0, s18, 0x2000
	s_nop 0
	global_load_lds_dwordx4 v[128:129], off
	s_waitcnt vmcnt(6)
	s_barrier
	s_setprio 1
	v_mfma_f32_16x16x32_bf16 v[52:55], v[202:205], v[160:163], v[52:55]
	v_mfma_f32_16x16x32_bf16 v[48:51], v[210:213], v[160:163], v[48:51]
	v_mfma_f32_16x16x32_bf16 v[36:39], v[202:205], v[178:181], v[36:39]
	v_mfma_f32_16x16x32_bf16 v[32:35], v[210:213], v[178:181], v[32:35]
	v_mfma_f32_16x16x32_bf16 v[20:23], v[202:205], v[186:189], v[20:23]
	v_mfma_f32_16x16x32_bf16 v[16:19], v[210:213], v[186:189], v[16:19]
	v_mfma_f32_16x16x32_bf16 v[4:7], v[202:205], v[194:197], v[4:7]
	v_mfma_f32_16x16x32_bf16 v[0:3], v[210:213], v[194:197], v[0:3]
	v_mfma_f32_16x16x32_bf16 v[52:55], v[206:209], v[174:177], v[52:55]
	v_mfma_f32_16x16x32_bf16 v[48:51], v[214:217], v[174:177], v[48:51]
	v_mfma_f32_16x16x32_bf16 v[36:39], v[206:209], v[182:185], v[36:39]
	v_mfma_f32_16x16x32_bf16 v[32:35], v[214:217], v[182:185], v[32:35]
	v_mfma_f32_16x16x32_bf16 v[20:23], v[206:209], v[190:193], v[20:23]
	v_mfma_f32_16x16x32_bf16 v[16:19], v[214:217], v[190:193], v[16:19]
	v_mfma_f32_16x16x32_bf16 v[4:7], v[206:209], v[198:201], v[4:7]
	v_mfma_f32_16x16x32_bf16 v[0:3], v[214:217], v[198:201], v[0:3]
	s_setprio 0
	s_add_i32 s81, s81, 2
	s_add_u32 s14, s14, 0x100
	s_addc_u32 s15, s15, 0
	s_add_u32 s68, s68, 0x100
	s_addc_u32 s69, s69, 0
	s_cmp_gt_u32 s81, 29
	s_barrier
	s_cbranch_scc0 .LBB0_107
	s_lshl_b32 s49, s8, 8
	v_add_u32_e32 v160, s49, v164
	v_ashrrev_i32_e32 v161, 31, v160
	v_lshl_add_u64 v[162:163], v[160:161], 2, s[22:23]
	global_load_dword v152, v[162:163], off offset:0
	global_load_dword v153, v[162:163], off offset:64
	global_load_dword v154, v[162:163], off offset:128
	global_load_dword v155, v[162:163], off offset:192
	global_load_dword v156, v[162:163], off offset:512
	global_load_dword v157, v[162:163], off offset:576
	global_load_dword v158, v[162:163], off offset:640
	global_load_dword v159, v[162:163], off offset:704
	s_cmp_lt_i32 s12, 24
	s_cselect_b64 s[14:15], -1, 0
	s_and_b64 s[14:15], s[14:15], s[44:45]
	s_cmp_lt_i32 s12, 12
	s_cselect_b32 s13, s46, 1.0
	v_mov_b32_e32 v236, s13
	v_mov_b64_e32 v[162:163], s[50:51]
	v_mad_i64_i32 v[162:163], s[16:17], v160, s76, v[162:163]
	s_lshl_b32 s68, s12, 9
	s_mov_b32 s69, 0
	v_lshl_add_u64 v[162:163], v[162:163], 0, s[68:69]
	v_lshl_add_u64 v[162:163], v[162:163], 0, s[42:43]
	v_lshl_add_u64 v[162:163], v[162:163], 0, v[142:143]
	s_mov_b32 s68, 0x48000
	s_mov_b32 s82, 0x168000
	s_mov_b32 s83, 0
	s_and_b64 vcc, exec, s[14:15]
	s_cbranch_vccz .Lq0_noropeld
	v_lshlrev_b32_e32 v230, 5, v160
	v_and_or_b32 v230, v230, s79, v165
	v_lshlrev_b32_e32 v230, 2, v230
	v_add_u32_e32 v231, 0x1000, v230
	v_add_u32_e32 v233, 0x4000, v230
	v_add_u32_e32 v234, 0x5000, v230
	global_load_dwordx4 v[174:177], v230, s[58:59] offset:0
	global_load_dwordx4 v[178:181], v230, s[58:59] offset:16
	global_load_dwordx4 v[182:185], v230, s[58:59] offset:2048
	global_load_dwordx4 v[186:189], v230, s[58:59] offset:2064
	global_load_dwordx4 v[190:193], v231, s[58:59] offset:0
	global_load_dwordx4 v[194:197], v231, s[58:59] offset:16
	global_load_dwordx4 v[198:201], v231, s[58:59] offset:2048
	global_load_dwordx4 v[202:205], v231, s[58:59] offset:2064
	global_load_dwordx4 v[206:209], v233, s[58:59] offset:0
	global_load_dwordx4 v[210:213], v233, s[58:59] offset:16
	global_load_dwordx4 v[214:217], v233, s[58:59] offset:2048
	global_load_dwordx4 v[218:221], v233, s[58:59] offset:2064
	global_load_dwordx4 v[222:225], v234, s[58:59] offset:0
	global_load_dwordx4 v[226:229], v234, s[58:59] offset:16
	global_load_dwordx4 v[128:131], v234, s[58:59] offset:2048
	global_load_dwordx4 v[132:135], v234, s[58:59] offset:2064
.Lq0_noropeld:
	s_waitcnt vmcnt(0)
	v_fmamk_f32 v152, v152, 0x3a000000, v173
	v_fmamk_f32 v153, v153, 0x3a000000, v173
	v_fmamk_f32 v154, v154, 0x3a000000, v173
	v_fmamk_f32 v155, v155, 0x3a000000, v173
	v_fmamk_f32 v156, v156, 0x3a000000, v173
	v_fmamk_f32 v157, v157, 0x3a000000, v173
	v_fmamk_f32 v158, v158, 0x3a000000, v173
	v_fmamk_f32 v159, v159, 0x3a000000, v173
	v_mul_f32_e32 v238, 0x4b800000, v152
	v_cmp_gt_f32_e32 vcc, s75, v152
	s_nop 1
	v_cndmask_b32_e32 v152, v152, v238, vcc
	v_rsq_f32_e32 v152, v152
	s_nop 0
	v_mul_f32_e32 v238, 0x45800000, v152
	v_cndmask_b32_e32 v152, v152, v238, vcc
	v_mul_f32_e32 v235, 0x4b800000, v153
	v_cmp_gt_f32_e32 vcc, s75, v153
	s_nop 1
	v_cndmask_b32_e32 v153, v153, v235, vcc
	v_rsq_f32_e32 v153, v153
	s_nop 0
	v_mul_f32_e32 v235, 0x45800000, v153
	v_cndmask_b32_e32 v153, v153, v235, vcc
	v_mul_f32_e32 v238, 0x4b800000, v154
	v_cmp_gt_f32_e32 vcc, s75, v154
	s_nop 1
	v_cndmask_b32_e32 v154, v154, v238, vcc
	v_rsq_f32_e32 v154, v154
	s_nop 0
	v_mul_f32_e32 v238, 0x45800000, v154
	v_cndmask_b32_e32 v154, v154, v238, vcc
	v_mul_f32_e32 v235, 0x4b800000, v155
	v_cmp_gt_f32_e32 vcc, s75, v155
	s_nop 1
	v_cndmask_b32_e32 v155, v155, v235, vcc
	v_rsq_f32_e32 v155, v155
	s_nop 0
	v_mul_f32_e32 v235, 0x45800000, v155
	v_cndmask_b32_e32 v155, v155, v235, vcc
	v_mul_f32_e32 v238, 0x4b800000, v156
	v_cmp_gt_f32_e32 vcc, s75, v156
	s_nop 1
	v_cndmask_b32_e32 v156, v156, v238, vcc
	v_rsq_f32_e32 v156, v156
	s_nop 0
	v_mul_f32_e32 v238, 0x45800000, v156
	v_cndmask_b32_e32 v156, v156, v238, vcc
	v_mul_f32_e32 v235, 0x4b800000, v157
	v_cmp_gt_f32_e32 vcc, s75, v157
	s_nop 1
	v_cndmask_b32_e32 v157, v157, v235, vcc
	v_rsq_f32_e32 v157, v157
	s_nop 0
	v_mul_f32_e32 v235, 0x45800000, v157
	v_cndmask_b32_e32 v157, v157, v235, vcc
	v_mul_f32_e32 v238, 0x4b800000, v158
	v_cmp_gt_f32_e32 vcc, s75, v158
	s_nop 1
	v_cndmask_b32_e32 v158, v158, v238, vcc
	v_rsq_f32_e32 v158, v158
	s_nop 0
	v_mul_f32_e32 v238, 0x45800000, v158
	v_cndmask_b32_e32 v158, v158, v238, vcc
	v_mul_f32_e32 v235, 0x4b800000, v159
	v_cmp_gt_f32_e32 vcc, s75, v159
	s_nop 1
	v_cndmask_b32_e32 v159, v159, v235, vcc
	v_rsq_f32_e32 v159, v159
	s_nop 0
	v_mul_f32_e32 v235, 0x45800000, v159
	v_cndmask_b32_e32 v159, v159, v235, vcc
	v_pk_mul_f32 v[124:125], v[124:125], v[152:153] op_sel:[0,0] op_sel_hi:[1,0]
	v_pk_mul_f32 v[126:127], v[126:127], v[152:153] op_sel:[0,0] op_sel_hi:[1,0]
	v_pk_mul_f32 v[120:121], v[120:121], v[152:153] op_sel:[0,0] op_sel_hi:[1,0]
	v_pk_mul_f32 v[122:123], v[122:123], v[152:153] op_sel:[0,0] op_sel_hi:[1,0]
	v_pk_mul_f32 v[116:117], v[116:117], v[152:153] op_sel:[0,0] op_sel_hi:[1,0]
	v_pk_mul_f32 v[118:119], v[118:119], v[152:153] op_sel:[0,0] op_sel_hi:[1,0]
	v_pk_mul_f32 v[112:113], v[112:113], v[152:153] op_sel:[0,0] op_sel_hi:[1,0]
	v_pk_mul_f32 v[114:115], v[114:115], v[152:153] op_sel:[0,0] op_sel_hi:[1,0]
	s_and_b64 vcc, exec, s[14:15]
	s_cbranch_vccz .Lq0_norope_0
	v_mul_f32_e32 v230, v120, v175
	v_mul_f32_e32 v231, v124, v175
	v_fma_f32 v124, v124, v174, -v230
	v_fma_f32 v120, v120, v174, v231
	v_mul_f32_e32 v233, v121, v177
	v_mul_f32_e32 v234, v125, v177
	v_fma_f32 v125, v125, v176, -v233
	v_fma_f32 v121, v121, v176, v234
	v_mul_f32_e32 v230, v122, v179
	v_mul_f32_e32 v231, v126, v179
	v_fma_f32 v126, v126, v178, -v230
	v_fma_f32 v122, v122, v178, v231
	v_mul_f32_e32 v233, v123, v181
	v_mul_f32_e32 v234, v127, v181
	v_fma_f32 v127, v127, v180, -v233
	v_fma_f32 v123, v123, v180, v234
	v_mul_f32_e32 v230, v112, v175
	v_mul_f32_e32 v231, v116, v175
	v_fma_f32 v116, v116, v174, -v230
	v_fma_f32 v112, v112, v174, v231
	v_mul_f32_e32 v233, v113, v177
	v_mul_f32_e32 v234, v117, v177
	v_fma_f32 v117, v117, v176, -v233
	v_fma_f32 v113, v113, v176, v234
	v_mul_f32_e32 v230, v114, v179
	v_mul_f32_e32 v231, v118, v179
	v_fma_f32 v118, v118, v178, -v230
	v_fma_f32 v114, v114, v178, v231
	v_mul_f32_e32 v233, v115, v181
	v_mul_f32_e32 v234, v119, v181
	v_fma_f32 v119, v119, v180, -v233
	v_fma_f32 v115, v115, v180, v234
.Lq0_norope_0:
	v_pk_mul_f32 v[124:125], v[124:125], v[236:237] op_sel_hi:[1,0]
	v_pk_mul_f32 v[126:127], v[126:127], v[236:237] op_sel_hi:[1,0]
	v_pk_mul_f32 v[120:121], v[120:121], v[236:237] op_sel_hi:[1,0]
	v_pk_mul_f32 v[122:123], v[122:123], v[236:237] op_sel_hi:[1,0]
	v_pk_mul_f32 v[116:117], v[116:117], v[236:237] op_sel_hi:[1,0]
	v_pk_mul_f32 v[118:119], v[118:119], v[236:237] op_sel_hi:[1,0]
	v_pk_mul_f32 v[112:113], v[112:113], v[236:237] op_sel_hi:[1,0]
	v_pk_mul_f32 v[114:115], v[114:115], v[236:237] op_sel_hi:[1,0]
	v_cvt_pk_bf16_f32 v124, v124, v125
	v_cvt_pk_bf16_f32 v125, v126, v127
	v_cvt_pk_bf16_f32 v120, v120, v121
	v_cvt_pk_bf16_f32 v121, v122, v123
	v_cvt_pk_bf16_f32 v116, v116, v117
	v_cvt_pk_bf16_f32 v117, v118, v119
	v_cvt_pk_bf16_f32 v112, v112, v113
	v_cvt_pk_bf16_f32 v113, v114, v115
	global_store_dwordx2 v[162:163], v[124:125], off offset:0
	global_store_dwordx2 v[162:163], v[120:121], off offset:32
	global_store_dwordx2 v[162:163], v[116:117], off offset:256
	global_store_dwordx2 v[162:163], v[112:113], off offset:288
	v_lshl_add_u64 v[162:163], v[162:163], 0, s[68:69]
	v_pk_mul_f32 v[108:109], v[108:109], v[152:153] op_sel:[0,1] op_sel_hi:[1,1]
	v_pk_mul_f32 v[110:111], v[110:111], v[152:153] op_sel:[0,1] op_sel_hi:[1,1]
	v_pk_mul_f32 v[104:105], v[104:105], v[152:153] op_sel:[0,1] op_sel_hi:[1,1]
	v_pk_mul_f32 v[106:107], v[106:107], v[152:153] op_sel:[0,1] op_sel_hi:[1,1]
	v_pk_mul_f32 v[100:101], v[100:101], v[152:153] op_sel:[0,1] op_sel_hi:[1,1]
	v_pk_mul_f32 v[102:103], v[102:103], v[152:153] op_sel:[0,1] op_sel_hi:[1,1]
	v_pk_mul_f32 v[96:97], v[96:97], v[152:153] op_sel:[0,1] op_sel_hi:[1,1]
	v_pk_mul_f32 v[98:99], v[98:99], v[152:153] op_sel:[0,1] op_sel_hi:[1,1]
	s_and_b64 vcc, exec, s[14:15]
	s_cbranch_vccz .Lq0_norope_1
	v_mul_f32_e32 v230, v104, v183
	v_mul_f32_e32 v231, v108, v183
	v_fma_f32 v108, v108, v182, -v230
	v_fma_f32 v104, v104, v182, v231
	v_mul_f32_e32 v233, v105, v185
	v_mul_f32_e32 v234, v109, v185
	v_fma_f32 v109, v109, v184, -v233
	v_fma_f32 v105, v105, v184, v234
	v_mul_f32_e32 v230, v106, v187
	v_mul_f32_e32 v231, v110, v187
	v_fma_f32 v110, v110, v186, -v230
	v_fma_f32 v106, v106, v186, v231
	v_mul_f32_e32 v233, v107, v189
	v_mul_f32_e32 v234, v111, v189
	v_fma_f32 v111, v111, v188, -v233
	v_fma_f32 v107, v107, v188, v234
	v_mul_f32_e32 v230, v96, v183
	v_mul_f32_e32 v231, v100, v183
	v_fma_f32 v100, v100, v182, -v230
	v_fma_f32 v96, v96, v182, v231
	v_mul_f32_e32 v233, v97, v185
	v_mul_f32_e32 v234, v101, v185
	v_fma_f32 v101, v101, v184, -v233
	v_fma_f32 v97, v97, v184, v234
	v_mul_f32_e32 v230, v98, v187
	v_mul_f32_e32 v231, v102, v187
	v_fma_f32 v102, v102, v186, -v230
	v_fma_f32 v98, v98, v186, v231
	v_mul_f32_e32 v233, v99, v189
	v_mul_f32_e32 v234, v103, v189
	v_fma_f32 v103, v103, v188, -v233
	v_fma_f32 v99, v99, v188, v234
.Lq0_norope_1:
	v_pk_mul_f32 v[108:109], v[108:109], v[236:237] op_sel_hi:[1,0]
	v_pk_mul_f32 v[110:111], v[110:111], v[236:237] op_sel_hi:[1,0]
	v_pk_mul_f32 v[104:105], v[104:105], v[236:237] op_sel_hi:[1,0]
	v_pk_mul_f32 v[106:107], v[106:107], v[236:237] op_sel_hi:[1,0]
	v_pk_mul_f32 v[100:101], v[100:101], v[236:237] op_sel_hi:[1,0]
	v_pk_mul_f32 v[102:103], v[102:103], v[236:237] op_sel_hi:[1,0]
	v_pk_mul_f32 v[96:97], v[96:97], v[236:237] op_sel_hi:[1,0]
	v_pk_mul_f32 v[98:99], v[98:99], v[236:237] op_sel_hi:[1,0]
	v_cvt_pk_bf16_f32 v108, v108, v109
	v_cvt_pk_bf16_f32 v109, v110, v111
	v_cvt_pk_bf16_f32 v104, v104, v105
	v_cvt_pk_bf16_f32 v105, v106, v107
	v_cvt_pk_bf16_f32 v100, v100, v101
	v_cvt_pk_bf16_f32 v101, v102, v103
	v_cvt_pk_bf16_f32 v96, v96, v97
	v_cvt_pk_bf16_f32 v97, v98, v99
	global_store_dwordx2 v[162:163], v[108:109], off offset:0
	global_store_dwordx2 v[162:163], v[104:105], off offset:32
	global_store_dwordx2 v[162:163], v[100:101], off offset:256
	global_store_dwordx2 v[162:163], v[96:97], off offset:288
	v_lshl_add_u64 v[162:163], v[162:163], 0, s[68:69]
	v_pk_mul_f32 v[92:93], v[92:93], v[154:155] op_sel:[0,0] op_sel_hi:[1,0]
	v_pk_mul_f32 v[94:95], v[94:95], v[154:155] op_sel:[0,0] op_sel_hi:[1,0]
	v_pk_mul_f32 v[88:89], v[88:89], v[154:155] op_sel:[0,0] op_sel_hi:[1,0]
	v_pk_mul_f32 v[90:91], v[90:91], v[154:155] op_sel:[0,0] op_sel_hi:[1,0]
	v_pk_mul_f32 v[84:85], v[84:85], v[154:155] op_sel:[0,0] op_sel_hi:[1,0]
	v_pk_mul_f32 v[86:87], v[86:87], v[154:155] op_sel:[0,0] op_sel_hi:[1,0]
	v_pk_mul_f32 v[80:81], v[80:81], v[154:155] op_sel:[0,0] op_sel_hi:[1,0]
	v_pk_mul_f32 v[82:83], v[82:83], v[154:155] op_sel:[0,0] op_sel_hi:[1,0]
	s_and_b64 vcc, exec, s[14:15]
	s_cbranch_vccz .Lq0_norope_2
	v_mul_f32_e32 v230, v88, v191
	v_mul_f32_e32 v231, v92, v191
	v_fma_f32 v92, v92, v190, -v230
	v_fma_f32 v88, v88, v190, v231
	v_mul_f32_e32 v233, v89, v193
	v_mul_f32_e32 v234, v93, v193
	v_fma_f32 v93, v93, v192, -v233
	v_fma_f32 v89, v89, v192, v234
	v_mul_f32_e32 v230, v90, v195
	v_mul_f32_e32 v231, v94, v195
	v_fma_f32 v94, v94, v194, -v230
	v_fma_f32 v90, v90, v194, v231
	v_mul_f32_e32 v233, v91, v197
	v_mul_f32_e32 v234, v95, v197
	v_fma_f32 v95, v95, v196, -v233
	v_fma_f32 v91, v91, v196, v234
	v_mul_f32_e32 v230, v80, v191
	v_mul_f32_e32 v231, v84, v191
	v_fma_f32 v84, v84, v190, -v230
	v_fma_f32 v80, v80, v190, v231
	v_mul_f32_e32 v233, v81, v193
	v_mul_f32_e32 v234, v85, v193
	v_fma_f32 v85, v85, v192, -v233
	v_fma_f32 v81, v81, v192, v234
	v_mul_f32_e32 v230, v82, v195
	v_mul_f32_e32 v231, v86, v195
	v_fma_f32 v86, v86, v194, -v230
	v_fma_f32 v82, v82, v194, v231
	v_mul_f32_e32 v233, v83, v197
	v_mul_f32_e32 v234, v87, v197
	v_fma_f32 v87, v87, v196, -v233
	v_fma_f32 v83, v83, v196, v234
.Lq0_norope_2:
	v_pk_mul_f32 v[92:93], v[92:93], v[236:237] op_sel_hi:[1,0]
	v_pk_mul_f32 v[94:95], v[94:95], v[236:237] op_sel_hi:[1,0]
	v_pk_mul_f32 v[88:89], v[88:89], v[236:237] op_sel_hi:[1,0]
	v_pk_mul_f32 v[90:91], v[90:91], v[236:237] op_sel_hi:[1,0]
	v_pk_mul_f32 v[84:85], v[84:85], v[236:237] op_sel_hi:[1,0]
	v_pk_mul_f32 v[86:87], v[86:87], v[236:237] op_sel_hi:[1,0]
	v_pk_mul_f32 v[80:81], v[80:81], v[236:237] op_sel_hi:[1,0]
	v_pk_mul_f32 v[82:83], v[82:83], v[236:237] op_sel_hi:[1,0]
	v_cvt_pk_bf16_f32 v92, v92, v93
	v_cvt_pk_bf16_f32 v93, v94, v95
	v_cvt_pk_bf16_f32 v88, v88, v89
	v_cvt_pk_bf16_f32 v89, v90, v91
	v_cvt_pk_bf16_f32 v84, v84, v85
	v_cvt_pk_bf16_f32 v85, v86, v87
	v_cvt_pk_bf16_f32 v80, v80, v81
	v_cvt_pk_bf16_f32 v81, v82, v83
	global_store_dwordx2 v[162:163], v[92:93], off offset:0
	global_store_dwordx2 v[162:163], v[88:89], off offset:32
	global_store_dwordx2 v[162:163], v[84:85], off offset:256
	global_store_dwordx2 v[162:163], v[80:81], off offset:288
	v_lshl_add_u64 v[162:163], v[162:163], 0, s[68:69]
	v_pk_mul_f32 v[76:77], v[76:77], v[154:155] op_sel:[0,1] op_sel_hi:[1,1]
	v_pk_mul_f32 v[78:79], v[78:79], v[154:155] op_sel:[0,1] op_sel_hi:[1,1]
	v_pk_mul_f32 v[72:73], v[72:73], v[154:155] op_sel:[0,1] op_sel_hi:[1,1]
	v_pk_mul_f32 v[74:75], v[74:75], v[154:155] op_sel:[0,1] op_sel_hi:[1,1]
	v_pk_mul_f32 v[68:69], v[68:69], v[154:155] op_sel:[0,1] op_sel_hi:[1,1]
	v_pk_mul_f32 v[70:71], v[70:71], v[154:155] op_sel:[0,1] op_sel_hi:[1,1]
	v_pk_mul_f32 v[64:65], v[64:65], v[154:155] op_sel:[0,1] op_sel_hi:[1,1]
	v_pk_mul_f32 v[66:67], v[66:67], v[154:155] op_sel:[0,1] op_sel_hi:[1,1]
	s_and_b64 vcc, exec, s[14:15]
	s_cbranch_vccz .Lq0_norope_3
	v_mul_f32_e32 v230, v72, v199
	v_mul_f32_e32 v231, v76, v199
	v_fma_f32 v76, v76, v198, -v230
	v_fma_f32 v72, v72, v198, v231
	v_mul_f32_e32 v233, v73, v201
	v_mul_f32_e32 v234, v77, v201
	v_fma_f32 v77, v77, v200, -v233
	v_fma_f32 v73, v73, v200, v234
	v_mul_f32_e32 v230, v74, v203
	v_mul_f32_e32 v231, v78, v203
	v_fma_f32 v78, v78, v202, -v230
	v_fma_f32 v74, v74, v202, v231
	v_mul_f32_e32 v233, v75, v205
	v_mul_f32_e32 v234, v79, v205
	v_fma_f32 v79, v79, v204, -v233
	v_fma_f32 v75, v75, v204, v234
	v_mul_f32_e32 v230, v64, v199
	v_mul_f32_e32 v231, v68, v199
	v_fma_f32 v68, v68, v198, -v230
	v_fma_f32 v64, v64, v198, v231
	v_mul_f32_e32 v233, v65, v201
	v_mul_f32_e32 v234, v69, v201
	v_fma_f32 v69, v69, v200, -v233
	v_fma_f32 v65, v65, v200, v234
	v_mul_f32_e32 v230, v66, v203
	v_mul_f32_e32 v231, v70, v203
	v_fma_f32 v70, v70, v202, -v230
	v_fma_f32 v66, v66, v202, v231
	v_mul_f32_e32 v233, v67, v205
	v_mul_f32_e32 v234, v71, v205
	v_fma_f32 v71, v71, v204, -v233
	v_fma_f32 v67, v67, v204, v234
.Lq0_norope_3:
	v_pk_mul_f32 v[76:77], v[76:77], v[236:237] op_sel_hi:[1,0]
	v_pk_mul_f32 v[78:79], v[78:79], v[236:237] op_sel_hi:[1,0]
	v_pk_mul_f32 v[72:73], v[72:73], v[236:237] op_sel_hi:[1,0]
	v_pk_mul_f32 v[74:75], v[74:75], v[236:237] op_sel_hi:[1,0]
	v_pk_mul_f32 v[68:69], v[68:69], v[236:237] op_sel_hi:[1,0]
	v_pk_mul_f32 v[70:71], v[70:71], v[236:237] op_sel_hi:[1,0]
	v_pk_mul_f32 v[64:65], v[64:65], v[236:237] op_sel_hi:[1,0]
	v_pk_mul_f32 v[66:67], v[66:67], v[236:237] op_sel_hi:[1,0]
	v_cvt_pk_bf16_f32 v76, v76, v77
	v_cvt_pk_bf16_f32 v77, v78, v79
	v_cvt_pk_bf16_f32 v72, v72, v73
	v_cvt_pk_bf16_f32 v73, v74, v75
	v_cvt_pk_bf16_f32 v68, v68, v69
	v_cvt_pk_bf16_f32 v69, v70, v71
	v_cvt_pk_bf16_f32 v64, v64, v65
	v_cvt_pk_bf16_f32 v65, v66, v67
	global_store_dwordx2 v[162:163], v[76:77], off offset:0
	global_store_dwordx2 v[162:163], v[72:73], off offset:32
	global_store_dwordx2 v[162:163], v[68:69], off offset:256
	global_store_dwordx2 v[162:163], v[64:65], off offset:288
	v_lshl_add_u64 v[162:163], v[162:163], 0, s[82:83]
	v_pk_mul_f32 v[60:61], v[60:61], v[156:157] op_sel:[0,0] op_sel_hi:[1,0]
	v_pk_mul_f32 v[62:63], v[62:63], v[156:157] op_sel:[0,0] op_sel_hi:[1,0]
	v_pk_mul_f32 v[56:57], v[56:57], v[156:157] op_sel:[0,0] op_sel_hi:[1,0]
	v_pk_mul_f32 v[58:59], v[58:59], v[156:157] op_sel:[0,0] op_sel_hi:[1,0]
	v_pk_mul_f32 v[52:53], v[52:53], v[156:157] op_sel:[0,0] op_sel_hi:[1,0]
	v_pk_mul_f32 v[54:55], v[54:55], v[156:157] op_sel:[0,0] op_sel_hi:[1,0]
	v_pk_mul_f32 v[48:49], v[48:49], v[156:157] op_sel:[0,0] op_sel_hi:[1,0]
	v_pk_mul_f32 v[50:51], v[50:51], v[156:157] op_sel:[0,0] op_sel_hi:[1,0]
	s_and_b64 vcc, exec, s[14:15]
	s_cbranch_vccz .Lq0_norope_4
	v_mul_f32_e32 v230, v56, v207
	v_mul_f32_e32 v231, v60, v207
	v_fma_f32 v60, v60, v206, -v230
	v_fma_f32 v56, v56, v206, v231
	v_mul_f32_e32 v233, v57, v209
	v_mul_f32_e32 v234, v61, v209
	v_fma_f32 v61, v61, v208, -v233
	v_fma_f32 v57, v57, v208, v234
	v_mul_f32_e32 v230, v58, v211
	v_mul_f32_e32 v231, v62, v211
	v_fma_f32 v62, v62, v210, -v230
	v_fma_f32 v58, v58, v210, v231
	v_mul_f32_e32 v233, v59, v213
	v_mul_f32_e32 v234, v63, v213
	v_fma_f32 v63, v63, v212, -v233
	v_fma_f32 v59, v59, v212, v234
	v_mul_f32_e32 v230, v48, v207
	v_mul_f32_e32 v231, v52, v207
	v_fma_f32 v52, v52, v206, -v230
	v_fma_f32 v48, v48, v206, v231
	v_mul_f32_e32 v233, v49, v209
	v_mul_f32_e32 v234, v53, v209
	v_fma_f32 v53, v53, v208, -v233
	v_fma_f32 v49, v49, v208, v234
	v_mul_f32_e32 v230, v50, v211
	v_mul_f32_e32 v231, v54, v211
	v_fma_f32 v54, v54, v210, -v230
	v_fma_f32 v50, v50, v210, v231
	v_mul_f32_e32 v233, v51, v213
	v_mul_f32_e32 v234, v55, v213
	v_fma_f32 v55, v55, v212, -v233
	v_fma_f32 v51, v51, v212, v234
.Lq0_norope_4:
	v_pk_mul_f32 v[60:61], v[60:61], v[236:237] op_sel_hi:[1,0]
	v_pk_mul_f32 v[62:63], v[62:63], v[236:237] op_sel_hi:[1,0]
	v_pk_mul_f32 v[56:57], v[56:57], v[236:237] op_sel_hi:[1,0]
	v_pk_mul_f32 v[58:59], v[58:59], v[236:237] op_sel_hi:[1,0]
	v_pk_mul_f32 v[52:53], v[52:53], v[236:237] op_sel_hi:[1,0]
	v_pk_mul_f32 v[54:55], v[54:55], v[236:237] op_sel_hi:[1,0]
	v_pk_mul_f32 v[48:49], v[48:49], v[236:237] op_sel_hi:[1,0]
	v_pk_mul_f32 v[50:51], v[50:51], v[236:237] op_sel_hi:[1,0]
	v_cvt_pk_bf16_f32 v60, v60, v61
	v_cvt_pk_bf16_f32 v61, v62, v63
	v_cvt_pk_bf16_f32 v56, v56, v57
	v_cvt_pk_bf16_f32 v57, v58, v59
	v_cvt_pk_bf16_f32 v52, v52, v53
	v_cvt_pk_bf16_f32 v53, v54, v55
	v_cvt_pk_bf16_f32 v48, v48, v49
	v_cvt_pk_bf16_f32 v49, v50, v51
	global_store_dwordx2 v[162:163], v[60:61], off offset:0
	global_store_dwordx2 v[162:163], v[56:57], off offset:32
	global_store_dwordx2 v[162:163], v[52:53], off offset:256
	global_store_dwordx2 v[162:163], v[48:49], off offset:288
	v_lshl_add_u64 v[162:163], v[162:163], 0, s[68:69]
	v_pk_mul_f32 v[44:45], v[44:45], v[156:157] op_sel:[0,1] op_sel_hi:[1,1]
	v_pk_mul_f32 v[46:47], v[46:47], v[156:157] op_sel:[0,1] op_sel_hi:[1,1]
	v_pk_mul_f32 v[40:41], v[40:41], v[156:157] op_sel:[0,1] op_sel_hi:[1,1]
	v_pk_mul_f32 v[42:43], v[42:43], v[156:157] op_sel:[0,1] op_sel_hi:[1,1]
	v_pk_mul_f32 v[36:37], v[36:37], v[156:157] op_sel:[0,1] op_sel_hi:[1,1]
	v_pk_mul_f32 v[38:39], v[38:39], v[156:157] op_sel:[0,1] op_sel_hi:[1,1]
	v_pk_mul_f32 v[32:33], v[32:33], v[156:157] op_sel:[0,1] op_sel_hi:[1,1]
	v_pk_mul_f32 v[34:35], v[34:35], v[156:157] op_sel:[0,1] op_sel_hi:[1,1]
	s_and_b64 vcc, exec, s[14:15]
	s_cbranch_vccz .Lq0_norope_5
	v_mul_f32_e32 v230, v40, v215
	v_mul_f32_e32 v231, v44, v215
	v_fma_f32 v44, v44, v214, -v230
	v_fma_f32 v40, v40, v214, v231
	v_mul_f32_e32 v233, v41, v217
	v_mul_f32_e32 v234, v45, v217
	v_fma_f32 v45, v45, v216, -v233
	v_fma_f32 v41, v41, v216, v234
	v_mul_f32_e32 v230, v42, v219
	v_mul_f32_e32 v231, v46, v219
	v_fma_f32 v46, v46, v218, -v230
	v_fma_f32 v42, v42, v218, v231
	v_mul_f32_e32 v233, v43, v221
	v_mul_f32_e32 v234, v47, v221
	v_fma_f32 v47, v47, v220, -v233
	v_fma_f32 v43, v43, v220, v234
	v_mul_f32_e32 v230, v32, v215
	v_mul_f32_e32 v231, v36, v215
	v_fma_f32 v36, v36, v214, -v230
	v_fma_f32 v32, v32, v214, v231
	v_mul_f32_e32 v233, v33, v217
	v_mul_f32_e32 v234, v37, v217
	v_fma_f32 v37, v37, v216, -v233
	v_fma_f32 v33, v33, v216, v234
	v_mul_f32_e32 v230, v34, v219
	v_mul_f32_e32 v231, v38, v219
	v_fma_f32 v38, v38, v218, -v230
	v_fma_f32 v34, v34, v218, v231
	v_mul_f32_e32 v233, v35, v221
	v_mul_f32_e32 v234, v39, v221
	v_fma_f32 v39, v39, v220, -v233
	v_fma_f32 v35, v35, v220, v234
.Lq0_norope_5:
	v_pk_mul_f32 v[44:45], v[44:45], v[236:237] op_sel_hi:[1,0]
	v_pk_mul_f32 v[46:47], v[46:47], v[236:237] op_sel_hi:[1,0]
	v_pk_mul_f32 v[40:41], v[40:41], v[236:237] op_sel_hi:[1,0]
	v_pk_mul_f32 v[42:43], v[42:43], v[236:237] op_sel_hi:[1,0]
	v_pk_mul_f32 v[36:37], v[36:37], v[236:237] op_sel_hi:[1,0]
	v_pk_mul_f32 v[38:39], v[38:39], v[236:237] op_sel_hi:[1,0]
	v_pk_mul_f32 v[32:33], v[32:33], v[236:237] op_sel_hi:[1,0]
	v_pk_mul_f32 v[34:35], v[34:35], v[236:237] op_sel_hi:[1,0]
	v_cvt_pk_bf16_f32 v44, v44, v45
	v_cvt_pk_bf16_f32 v45, v46, v47
	v_cvt_pk_bf16_f32 v40, v40, v41
	v_cvt_pk_bf16_f32 v41, v42, v43
	v_cvt_pk_bf16_f32 v36, v36, v37
	v_cvt_pk_bf16_f32 v37, v38, v39
	v_cvt_pk_bf16_f32 v32, v32, v33
	v_cvt_pk_bf16_f32 v33, v34, v35
	global_store_dwordx2 v[162:163], v[44:45], off offset:0
	global_store_dwordx2 v[162:163], v[40:41], off offset:32
	global_store_dwordx2 v[162:163], v[36:37], off offset:256
	global_store_dwordx2 v[162:163], v[32:33], off offset:288
	v_lshl_add_u64 v[162:163], v[162:163], 0, s[68:69]
	v_pk_mul_f32 v[28:29], v[28:29], v[158:159] op_sel:[0,0] op_sel_hi:[1,0]
	v_pk_mul_f32 v[30:31], v[30:31], v[158:159] op_sel:[0,0] op_sel_hi:[1,0]
	v_pk_mul_f32 v[24:25], v[24:25], v[158:159] op_sel:[0,0] op_sel_hi:[1,0]
	v_pk_mul_f32 v[26:27], v[26:27], v[158:159] op_sel:[0,0] op_sel_hi:[1,0]
	v_pk_mul_f32 v[20:21], v[20:21], v[158:159] op_sel:[0,0] op_sel_hi:[1,0]
	v_pk_mul_f32 v[22:23], v[22:23], v[158:159] op_sel:[0,0] op_sel_hi:[1,0]
	v_pk_mul_f32 v[16:17], v[16:17], v[158:159] op_sel:[0,0] op_sel_hi:[1,0]
	v_pk_mul_f32 v[18:19], v[18:19], v[158:159] op_sel:[0,0] op_sel_hi:[1,0]
	s_and_b64 vcc, exec, s[14:15]
	s_cbranch_vccz .Lq0_norope_6
	v_mul_f32_e32 v230, v24, v223
	v_mul_f32_e32 v231, v28, v223
	v_fma_f32 v28, v28, v222, -v230
	v_fma_f32 v24, v24, v222, v231
	v_mul_f32_e32 v233, v25, v225
	v_mul_f32_e32 v234, v29, v225
	v_fma_f32 v29, v29, v224, -v233
	v_fma_f32 v25, v25, v224, v234
	v_mul_f32_e32 v230, v26, v227
	v_mul_f32_e32 v231, v30, v227
	v_fma_f32 v30, v30, v226, -v230
	v_fma_f32 v26, v26, v226, v231
	v_mul_f32_e32 v233, v27, v229
	v_mul_f32_e32 v234, v31, v229
	v_fma_f32 v31, v31, v228, -v233
	v_fma_f32 v27, v27, v228, v234
	v_mul_f32_e32 v230, v16, v223
	v_mul_f32_e32 v231, v20, v223
	v_fma_f32 v20, v20, v222, -v230
	v_fma_f32 v16, v16, v222, v231
	v_mul_f32_e32 v233, v17, v225
	v_mul_f32_e32 v234, v21, v225
	v_fma_f32 v21, v21, v224, -v233
	v_fma_f32 v17, v17, v224, v234
	v_mul_f32_e32 v230, v18, v227
	v_mul_f32_e32 v231, v22, v227
	v_fma_f32 v22, v22, v226, -v230
	v_fma_f32 v18, v18, v226, v231
	v_mul_f32_e32 v233, v19, v229
	v_mul_f32_e32 v234, v23, v229
	v_fma_f32 v23, v23, v228, -v233
	v_fma_f32 v19, v19, v228, v234
.Lq0_norope_6:
	v_pk_mul_f32 v[28:29], v[28:29], v[236:237] op_sel_hi:[1,0]
	v_pk_mul_f32 v[30:31], v[30:31], v[236:237] op_sel_hi:[1,0]
	v_pk_mul_f32 v[24:25], v[24:25], v[236:237] op_sel_hi:[1,0]
	v_pk_mul_f32 v[26:27], v[26:27], v[236:237] op_sel_hi:[1,0]
	v_pk_mul_f32 v[20:21], v[20:21], v[236:237] op_sel_hi:[1,0]
	v_pk_mul_f32 v[22:23], v[22:23], v[236:237] op_sel_hi:[1,0]
	v_pk_mul_f32 v[16:17], v[16:17], v[236:237] op_sel_hi:[1,0]
	v_pk_mul_f32 v[18:19], v[18:19], v[236:237] op_sel_hi:[1,0]
	v_cvt_pk_bf16_f32 v28, v28, v29
	v_cvt_pk_bf16_f32 v29, v30, v31
	v_cvt_pk_bf16_f32 v24, v24, v25
	v_cvt_pk_bf16_f32 v25, v26, v27
	v_cvt_pk_bf16_f32 v20, v20, v21
	v_cvt_pk_bf16_f32 v21, v22, v23
	v_cvt_pk_bf16_f32 v16, v16, v17
	v_cvt_pk_bf16_f32 v17, v18, v19
	global_store_dwordx2 v[162:163], v[28:29], off offset:0
	global_store_dwordx2 v[162:163], v[24:25], off offset:32
	global_store_dwordx2 v[162:163], v[20:21], off offset:256
	global_store_dwordx2 v[162:163], v[16:17], off offset:288
	v_lshl_add_u64 v[162:163], v[162:163], 0, s[68:69]
	v_pk_mul_f32 v[12:13], v[12:13], v[158:159] op_sel:[0,1] op_sel_hi:[1,1]
	v_pk_mul_f32 v[14:15], v[14:15], v[158:159] op_sel:[0,1] op_sel_hi:[1,1]
	v_pk_mul_f32 v[8:9], v[8:9], v[158:159] op_sel:[0,1] op_sel_hi:[1,1]
	v_pk_mul_f32 v[10:11], v[10:11], v[158:159] op_sel:[0,1] op_sel_hi:[1,1]
	v_pk_mul_f32 v[4:5], v[4:5], v[158:159] op_sel:[0,1] op_sel_hi:[1,1]
	v_pk_mul_f32 v[6:7], v[6:7], v[158:159] op_sel:[0,1] op_sel_hi:[1,1]
	v_pk_mul_f32 v[0:1], v[0:1], v[158:159] op_sel:[0,1] op_sel_hi:[1,1]
	v_pk_mul_f32 v[2:3], v[2:3], v[158:159] op_sel:[0,1] op_sel_hi:[1,1]
	s_and_b64 vcc, exec, s[14:15]
	s_cbranch_vccz .Lq0_norope_7
	v_mul_f32_e32 v230, v8, v129
	v_mul_f32_e32 v231, v12, v129
	v_fma_f32 v12, v12, v128, -v230
	v_fma_f32 v8, v8, v128, v231
	v_mul_f32_e32 v233, v9, v131
	v_mul_f32_e32 v234, v13, v131
	v_fma_f32 v13, v13, v130, -v233
	v_fma_f32 v9, v9, v130, v234
	v_mul_f32_e32 v230, v10, v133
	v_mul_f32_e32 v231, v14, v133
	v_fma_f32 v14, v14, v132, -v230
	v_fma_f32 v10, v10, v132, v231
	v_mul_f32_e32 v233, v11, v135
	v_mul_f32_e32 v234, v15, v135
	v_fma_f32 v15, v15, v134, -v233
	v_fma_f32 v11, v11, v134, v234
	v_mul_f32_e32 v230, v0, v129
	v_mul_f32_e32 v231, v4, v129
	v_fma_f32 v4, v4, v128, -v230
	v_fma_f32 v0, v0, v128, v231
	v_mul_f32_e32 v233, v1, v131
	v_mul_f32_e32 v234, v5, v131
	v_fma_f32 v5, v5, v130, -v233
	v_fma_f32 v1, v1, v130, v234
	v_mul_f32_e32 v230, v2, v133
	v_mul_f32_e32 v231, v6, v133
	v_fma_f32 v6, v6, v132, -v230
	v_fma_f32 v2, v2, v132, v231
	v_mul_f32_e32 v233, v3, v135
	v_mul_f32_e32 v234, v7, v135
	v_fma_f32 v7, v7, v134, -v233
	v_fma_f32 v3, v3, v134, v234
.Lq0_norope_7:
	v_pk_mul_f32 v[12:13], v[12:13], v[236:237] op_sel_hi:[1,0]
	v_pk_mul_f32 v[14:15], v[14:15], v[236:237] op_sel_hi:[1,0]
	v_pk_mul_f32 v[8:9], v[8:9], v[236:237] op_sel_hi:[1,0]
	v_pk_mul_f32 v[10:11], v[10:11], v[236:237] op_sel_hi:[1,0]
	v_pk_mul_f32 v[4:5], v[4:5], v[236:237] op_sel_hi:[1,0]
	v_pk_mul_f32 v[6:7], v[6:7], v[236:237] op_sel_hi:[1,0]
	v_pk_mul_f32 v[0:1], v[0:1], v[236:237] op_sel_hi:[1,0]
	v_pk_mul_f32 v[2:3], v[2:3], v[236:237] op_sel_hi:[1,0]
	v_cvt_pk_bf16_f32 v12, v12, v13
	v_cvt_pk_bf16_f32 v13, v14, v15
	v_cvt_pk_bf16_f32 v8, v8, v9
	v_cvt_pk_bf16_f32 v9, v10, v11
	v_cvt_pk_bf16_f32 v4, v4, v5
	v_cvt_pk_bf16_f32 v5, v6, v7
	v_cvt_pk_bf16_f32 v0, v0, v1
	v_cvt_pk_bf16_f32 v1, v2, v3
	global_store_dwordx2 v[162:163], v[12:13], off offset:0
	global_store_dwordx2 v[162:163], v[8:9], off offset:32
	global_store_dwordx2 v[162:163], v[4:5], off offset:256
	global_store_dwordx2 v[162:163], v[0:1], off offset:288
	s_and_b64 vcc, exec, s[6:7]
	s_mov_b32 s12, s48
	s_mov_b32 s8, s54
	s_mov_b64 s[16:17], s[66:67]
	s_mov_b64 s[14:15], s[64:65]
	s_cbranch_vccnz .LBB0_164
	s_branch .LBB0_104
